# dilated chunk loop: branchy per-chunk descriptor code replaced by straight-line s_cselect form (same values)
# speedup vs baseline: 1.0107x; 1.0071x over previous
.LBB0_663:
	s_add_i32 s69, s70, 1
	s_cmp_ge_u32 s69, s49
	s_cselect_b64 s[12:13], -1, 0
	s_and_b64 vcc, exec, s[12:13]
	s_waitcnt vmcnt(7)
	ds_write_b128 v215, v[160:163]
	s_waitcnt vmcnt(6)
	ds_write_b128 v216, v[164:167] offset:4608
	s_waitcnt vmcnt(5)
	ds_write_b128 v215, v[168:171] offset:1152
	s_waitcnt vmcnt(4)
	ds_write_b128 v216, v[172:175] offset:5120
	s_waitcnt vmcnt(3)
	ds_write_b128 v215, v[176:179] offset:2304
	s_waitcnt vmcnt(2)
	ds_write_b128 v216, v[180:183] offset:5632
	s_waitcnt vmcnt(1)
	ds_write_b128 v215, v[184:187] offset:3456
	s_waitcnt vmcnt(0)
	ds_write_b128 v216, v[188:191] offset:6144
	s_cbranch_vccnz .LBB0_677
	s_cmp_ge_u32 s69, s47
	s_cbranch_scc0 .Ldd_f16
	s_cmp_ge_u32 s69, s6
	s_cselect_b32 s0, s6, s47
	s_cselect_b32 s1, s51, s64
	s_cselect_b32 s3, 1, 4
	s_cselect_b32 s14, 0, s24
	s_sub_i32 s0, s0, s69
	s_lshl_b32 s0, s0, 5
	s_add_i32 s2, s0, s1

.LBB0_677:
	s_cmp_ge_u32 s70, s47
	s_cbranch_scc0 .Ldd_s16
	s_cmp_ge_u32 s70, s6
	s_cselect_b64 s[16:17], -1, 0
	s_sub_i32 s0, s47, s70
	s_lshl_b32 s0, s0, 5
	s_add_i32 s0, s0, s64
	s_cmp_ge_u32 s70, s6
	s_cselect_b32 s71, s66, s0
	s_mov_b64 s[14:15], -1
	s_mov_b64 s[2:3], -1
	s_mov_b64 s[0:1], 0
	s_waitcnt lgkmcnt(9)
	v_cndmask_b32_e64 v0, v205, v221, s[16:17]
	v_cndmask_b32_e64 v16, v222, v223, s[16:17]

.Ldd_f16:
	s_sub_i32 s0, s45, s69
	s_lshl_b32 s0, s0, 5
	s_add_i32 s1, s67, s68
	s_cmp_gt_u32 s69, s46
	s_cselect_b32 s2, s1, s0
	s_cselect_b32 s14, s23, s19
	s_mov_b32 s3, 16
	s_branch .LBB0_676
.Ldd_s16:
	s_sub_i32 s0, s45, s70
	s_sub_i32 s1, s65, s70
	s_cmp_gt_u32 s70, s46
	s_cselect_b32 s0, s1, s0
	s_cselect_b64 s[14:15], -1, 0
	s_cselect_b64 s[2:3], 0, -1
	s_lshl_b32 s71, s0, 5
	s_mov_b64 s[0:1], -1
	s_waitcnt lgkmcnt(9)
	v_mov_b32_e32 v0, v220
	v_mov_b32_e32 v16, v220
	s_branch .LBB0_697
